# deferred conversion of layer-1 FFN gate/down weights (inside the HGRN2 phase) spread over all 256 workgroups instead of only the 128 without a prompt unit
# speedup vs baseline: 1.0082x; 1.0028x over previous
.LBB0_3561:
	s_mov_b64 s[14:15], 0
	v_readlane_b32 s6, v255, 9
	s_and_b64 s[4:5], s[34:35], s[14:15]
	v_readlane_b32 s7, v255, 10
	s_add_i32 s3, s6, 0xfffffc00
	s_mov_b32 s8, s6
	s_and_b64 s[6:7], s[14:15], exec
	s_cselect_b32 s3, s3, s8
	s_cmpk_gt_i32 s3, 0x2aff
	s_cselect_b64 s[6:7], -1, 0
	s_or_b64 s[4:5], s[4:5], s[6:7]
	s_and_b64 vcc, exec, s[4:5]
	s_cbranch_vccnz .LBB0_3566
	s_lshl_b32 s4, s91, 14
	s_add_i32 s6, s4, 0
	v_lshlrev_b32_e32 v2, 2, v0
	s_and_b64 s[4:5], s[14:15], exec
	v_and_b32_e32 v16, 60, v2
	v_and_b32_e32 v2, 0x60, v116
	v_readlane_b32 s4, v255, 11
	v_add_u32_e32 v5, s6, v2
	v_lshlrev_b32_e32 v2, 4, v31
	v_readlane_b32 s5, v255, 12
	v_mov_b32_e32 v3, 0
	v_add_u32_e32 v17, s6, v2
	v_mul_u32_u24_e32 v18, 0x88, v29
	s_cselect_b32 s8, 0x400, s4
	v_mul_u32_u24_e32 v15, 0x88, v16
	v_lshl_add_u64 v[6:7], s[38:39], 0, v[2:3]
	s_mov_b64 s[4:5], 0x2c200000
	s_lshl_b32 s9, s3, 6
	v_lshlrev_b32_e32 v2, 2, v16
	v_add_u32_e32 v16, v17, v18
	v_lshlrev_b32_e32 v4, 3, v31
	v_lshl_add_u64 v[6:7], v[6:7], 0, s[4:5]
	v_or_b32_e32 v8, 8, v29
	v_or_b32_e32 v9, 16, v29
	v_or_b32_e32 v10, 24, v29
	v_or_b32_e32 v11, 32, v29
	v_or_b32_e32 v12, 40, v29
	v_or_b32_e32 v13, 48, v29
	v_or_b32_e32 v14, 56, v29
	s_lshl_b32 s10, s8, 6
	s_mov_b32 s11, 0xac00000
	s_mov_b32 s12, 0xac04000
	s_mov_b32 s13, 0xac08000
	s_mov_b32 s14, 0xac0c000
	s_mov_b32 s15, 0xac10000
	s_mov_b32 s16, 0xac14000
	s_mov_b32 s17, 0xac18000
	s_mov_b32 s18, 0xac1c000
	s_mov_b32 s19, 0xac20000
	s_mov_b32 s20, 0xac24000
	s_mov_b32 s21, 0xac28000
	s_mov_b32 s22, 0xac2c000
	s_mov_b32 s23, 0xac30000
	s_mov_b32 s24, 0xac34000
	s_mov_b32 s25, 0xac38000
	s_mov_b32 s26, 0xac3c000
	v_add_u32_e32 v15, v5, v15
	s_movk_i32 s27, 0x5600
	v_add_u32_e32 v5, 0x880, v16
	v_add_u32_e32 v17, 0xcc0, v16
	v_add_u32_e32 v18, 0x1100, v16
	v_add_u32_e32 v19, 0x1540, v16
	v_add_u32_e32 v20, 0x1980, v16
	v_add_u32_e32 v21, 0x1dc0, v16
	s_mov_b32 s28, s9
	s_mov_b32 s29, s3
